# layer-1 weight-conversion store loops: removed stale vmcnt(4)/vmcnt(3) waits that throttled the bf16 stores
# baseline (speedup 1.0000x reference)
; __device__ void phase_wconv(PRef p, int l, float* sm) {
;     ...
;       for (int e = tid; e < 4096; e += 256) {
;         int jj = e >> 6, i = e & 63;
;         jb.dst[(size_t)(nt * 64 + jj) * jb.K + kt * 64 + i] = f2bf(sm[i * 65 + jj]);
;       }
.LBB0_216:
	s_nop 0
	v_ashrrev_i32_e32 v16, 6, v13
	v_ashrrev_i32_e32 v17, 6, v12
	v_lshl_add_u32 v18, v17, 2, v5
	v_lshl_add_u32 v19, v16, 2, v5
	ds_read_b32 v18, v18
	ds_read_b32 v19, v19
	v_add_u32_e32 v16, s0, v16
	s_nop 0
	v_add_u32_e32 v20, s19, v17
	v_ashrrev_i32_e32 v21, 31, v20
	v_add_u32_e32 v15, -2, v15
	s_waitcnt lgkmcnt(0)
	v_cvt_pk_bf16_f32 v22, v18, v19
	v_ashrrev_i32_e32 v19, 31, v16
	v_mad_u64_u32 v[16:17], vcc, s86, v16, 0
	v_mov_b32_e32 v18, v17
	v_mad_u64_u32 v[18:19], vcc, s86, v19, v[18:19]
	v_mov_b32_e32 v17, v18
	v_mad_u64_u32 v[18:19], vcc, s37, v20, 0
	v_mov_b32_e32 v20, v19
	v_mad_u64_u32 v[20:21], vcc, s37, v21, v[20:21]
	v_mov_b32_e32 v19, v20
	v_cmp_eq_u32_e32 vcc, 0, v15
	v_lshl_add_u64 v[18:19], v[18:19], 1, v[10:11]
	v_add_u32_e32 v13, 0x200, v13
	v_add_u32_e32 v12, 0x200, v12
	s_or_b64 s[94:95], vcc, s[94:95]
	v_lshl_add_u64 v[16:17], v[16:17], 1, v[10:11]
	global_store_short v[18:19], v22, off
	global_store_short_d16_hi v[16:17], v22, off
	s_andn2_b64 exec, exec, s[94:95]
	s_cbranch_execnz .LBB0_216
	s_or_b64 exec, exec, s[94:95]
	s_orn2_b64 s[94:95], s[8:9], exec
	v_mov_b32_e32 v12, v14

; __device__ void phase_wconv(PRef p, int l, float* sm) {
;     ...
;       for (int e = tid; e < 4096; e += 256) {
;         int jj = e >> 6, i = e & 63;
;         jb.dst[(size_t)(nt * 64 + jj) * jb.K + kt * 64 + i] = f2bf(sm[i * 65 + jj]);
;       }
.LBB0_220:
	v_ashrrev_i32_e32 v13, 6, v12
	v_add_u32_e32 v15, 0x100, v12
	s_nop 0
	v_lshl_add_u32 v16, v13, 2, v5
	v_cmp_lt_i32_e32 vcc, s82, v12
	v_add_u32_e32 v13, s19, v13
	v_mov_b32_e32 v12, v15
	ds_read_b32 v15, v16
	v_mad_u64_u32 v[16:17], s[0:1], v13, s37, 0
	v_ashrrev_i32_e32 v19, 31, v13
	v_mov_b32_e32 v18, v17
	v_mad_u64_u32 v[18:19], s[0:1], v19, s37, v[18:19]
	v_mov_b32_e32 v17, v18
	s_or_b64 s[62:63], vcc, s[62:63]
	v_lshl_add_u64 v[16:17], v[16:17], 1, v[10:11]
	s_waitcnt lgkmcnt(0)
	v_cvt_pk_bf16_f32 v13, v15, s0
	global_store_short v[16:17], v13, off
	s_andn2_b64 exec, exec, s[62:63]
	s_cbranch_execnz .LBB0_220
	s_branch .LBB0_205
